# sample attention: query rows unpacked to f32 once at staging (LDS), QK inner loop is pure f32 fmac
# speedup vs baseline: 1.0153x; 1.0008x over previous
.LBB0_693:
	s_or_b64 exec, exec, s[4:5]
	s_add_i32 s4, s17, 1
	v_cvt_f32_u32_e32 v4, s4
	s_waitcnt lgkmcnt(0)
	s_lshl_b32 s4, s95, 1
	s_add_i32 s4, s4, 0xffff0000
	v_lshlrev_b32_e32 v10, 16, v0
	v_and_b32_e32 v11, 0xffff0000, v0
	v_lshlrev_b32_e32 v12, 16, v1
	v_and_b32_e32 v13, 0xffff0000, v1
	v_lshlrev_b32_e32 v14, 16, v2
	v_and_b32_e32 v15, 0xffff0000, v2
	v_lshlrev_b32_e32 v16, 16, v3
	v_and_b32_e32 v17, 0xffff0000, v3
	v_lshl_add_u32 v18, v108, 5, s4
	ds_write_b128 v18, v[10:13]
	ds_write_b128 v18, v[14:17] offset:16
	s_waitcnt lgkmcnt(0)
	s_barrier
	v_mul_f32_e32 v8, -0.5, v4
	ds_read_b32 v0, v46
	ds_read_b32 v1, v47
	ds_read_b32 v2, v48
	ds_read_b32 v3, v49
	ds_read_b32 v4, v50
	ds_read_b32 v5, v51
	ds_read_b32 v6, v52
	ds_read_b32 v7, v53
	v_exp_f32_e32 v14, v8
	s_lshl_b32 s4, s17, 6
	s_lshl_b32 s30, s4, 1
	v_lshl_add_u64 v[8:9], v[36:37], 0, s[30:31]
	s_mov_b32 s4, 0
	s_lshl_b32 s30, s95, 1
	s_add_i32 s30, s30, 0xffff0000
	v_mov_b32_e32 v15, s30
	v_mov_b32_e32 v32, v56
	v_mov_b32_e32 v33, v57
	v_add_u32_e32 v34, 0x8800, v58
	v_mov_b32_e32 v176, 0
	v_mov_b32_e32 v177, 0
	v_mov_b32_e32 v178, 0
	v_mov_b32_e32 v179, 0
	v_mov_b32_e32 v180, 0
	v_mov_b32_e32 v181, 0
	v_mov_b32_e32 v182, 0
	v_mov_b32_e32 v183, 0
	v_mov_b32_e32 v184, 0
	v_mov_b32_e32 v185, 0
	v_mov_b32_e32 v186, 0
	v_mov_b32_e32 v187, 0
	v_mov_b32_e32 v188, 0
	v_mov_b32_e32 v189, 0
	v_mov_b32_e32 v190, 0
	v_mov_b32_e32 v191, 0
	v_mov_b32_e32 v192, 0
	v_mov_b32_e32 v193, 0
	v_mov_b32_e32 v194, 0
	v_mov_b32_e32 v195, 0
	v_mov_b32_e32 v196, 0
	v_mov_b32_e32 v197, 0
	v_mov_b32_e32 v198, 0
	v_mov_b32_e32 v199, 0
	ds_read_b128 v[60:63], v32 offset:0
	ds_read_b128 v[64:67], v32 offset:16
	ds_read_b128 v[68:71], v33 offset:0
	ds_read_b128 v[72:75], v33 offset:16
	ds_read_b128 v[76:79], v34 offset:0
	ds_read_b128 v[80:83], v34 offset:16
	ds_read_b128 v[24:27], v15 offset:0
	ds_read_b128 v[28:31], v15 offset:16
	s_mov_b32 s17, 0
.Lsm_qk:
	ds_read_b128 v[84:87], v32 offset:32
	ds_read_b128 v[88:91], v32 offset:48
	ds_read_b128 v[92:95], v33 offset:32
	ds_read_b128 v[96:99], v33 offset:48
	ds_read_b128 v[100:103], v34 offset:32
	ds_read_b128 v[104:107], v34 offset:48
	ds_read_b128 v[16:19], v15 offset:256
	ds_read_b128 v[20:23], v15 offset:272
	s_waitcnt lgkmcnt(8)
	v_fmac_f32_e32 v176, v60, v24
	v_fmac_f32_e32 v177, v68, v24
	v_fmac_f32_e32 v178, v76, v24
	v_fmac_f32_e32 v176, v61, v25
	v_fmac_f32_e32 v177, v69, v25
	v_fmac_f32_e32 v178, v77, v25
	v_fmac_f32_e32 v176, v62, v26
	v_fmac_f32_e32 v177, v70, v26
	v_fmac_f32_e32 v178, v78, v26
	v_fmac_f32_e32 v176, v63, v27
	v_fmac_f32_e32 v177, v71, v27
	v_fmac_f32_e32 v178, v79, v27
	v_fmac_f32_e32 v176, v64, v28
	v_fmac_f32_e32 v177, v72, v28
	v_fmac_f32_e32 v178, v80, v28
	v_fmac_f32_e32 v176, v65, v29
	v_fmac_f32_e32 v177, v73, v29
	v_fmac_f32_e32 v178, v81, v29
	v_fmac_f32_e32 v176, v66, v30
	v_fmac_f32_e32 v177, v74, v30
	v_fmac_f32_e32 v178, v82, v30
	v_fmac_f32_e32 v176, v67, v31
	v_fmac_f32_e32 v177, v75, v31
	v_fmac_f32_e32 v178, v83, v31
	ds_read_b128 v[24:27], v15 offset:512
	ds_read_b128 v[28:31], v15 offset:528
	s_waitcnt lgkmcnt(2)
	v_fmac_f32_e32 v179, v60, v16
	v_fmac_f32_e32 v180, v68, v16
	v_fmac_f32_e32 v181, v76, v16
	v_fmac_f32_e32 v179, v61, v17
	v_fmac_f32_e32 v180, v69, v17
	v_fmac_f32_e32 v181, v77, v17
	v_fmac_f32_e32 v179, v62, v18
	v_fmac_f32_e32 v180, v70, v18
	v_fmac_f32_e32 v181, v78, v18
	v_fmac_f32_e32 v179, v63, v19
	v_fmac_f32_e32 v180, v71, v19
	v_fmac_f32_e32 v181, v79, v19
	v_fmac_f32_e32 v179, v64, v20
	v_fmac_f32_e32 v180, v72, v20
	v_fmac_f32_e32 v181, v80, v20
	v_fmac_f32_e32 v179, v65, v21
	v_fmac_f32_e32 v180, v73, v21
	v_fmac_f32_e32 v181, v81, v21
	v_fmac_f32_e32 v179, v66, v22
	v_fmac_f32_e32 v180, v74, v22
	v_fmac_f32_e32 v181, v82, v22
	v_fmac_f32_e32 v179, v67, v23
	v_fmac_f32_e32 v180, v75, v23
	v_fmac_f32_e32 v181, v83, v23
	ds_read_b128 v[16:19], v15 offset:768
	ds_read_b128 v[20:23], v15 offset:784
	s_waitcnt lgkmcnt(2)
	v_fmac_f32_e32 v182, v60, v24
	v_fmac_f32_e32 v183, v68, v24
	v_fmac_f32_e32 v184, v76, v24
	v_fmac_f32_e32 v182, v61, v25
	v_fmac_f32_e32 v183, v69, v25
	v_fmac_f32_e32 v184, v77, v25
	v_fmac_f32_e32 v182, v62, v26
	v_fmac_f32_e32 v183, v70, v26
	v_fmac_f32_e32 v184, v78, v26
	v_fmac_f32_e32 v182, v63, v27
	v_fmac_f32_e32 v183, v71, v27
	v_fmac_f32_e32 v184, v79, v27
	v_fmac_f32_e32 v182, v64, v28
	v_fmac_f32_e32 v183, v72, v28
	v_fmac_f32_e32 v184, v80, v28
	v_fmac_f32_e32 v182, v65, v29
	v_fmac_f32_e32 v183, v73, v29
	v_fmac_f32_e32 v184, v81, v29
	v_fmac_f32_e32 v182, v66, v30
	v_fmac_f32_e32 v183, v74, v30
	v_fmac_f32_e32 v184, v82, v30
	v_fmac_f32_e32 v182, v67, v31
	v_fmac_f32_e32 v183, v75, v31
	v_fmac_f32_e32 v184, v83, v31
	ds_read_b128 v[24:27], v15 offset:1024
	ds_read_b128 v[28:31], v15 offset:1040
	s_waitcnt lgkmcnt(2)
	v_fmac_f32_e32 v185, v60, v16
	v_fmac_f32_e32 v186, v68, v16
	v_fmac_f32_e32 v187, v76, v16
	v_fmac_f32_e32 v185, v61, v17
	v_fmac_f32_e32 v186, v69, v17
	v_fmac_f32_e32 v187, v77, v17
	v_fmac_f32_e32 v185, v62, v18
	v_fmac_f32_e32 v186, v70, v18
	v_fmac_f32_e32 v187, v78, v18
	v_fmac_f32_e32 v185, v63, v19
	v_fmac_f32_e32 v186, v71, v19
	v_fmac_f32_e32 v187, v79, v19
	v_fmac_f32_e32 v185, v64, v20
	v_fmac_f32_e32 v186, v72, v20
	v_fmac_f32_e32 v187, v80, v20
	v_fmac_f32_e32 v185, v65, v21
	v_fmac_f32_e32 v186, v73, v21
	v_fmac_f32_e32 v187, v81, v21
	v_fmac_f32_e32 v185, v66, v22
	v_fmac_f32_e32 v186, v74, v22
	v_fmac_f32_e32 v187, v82, v22
	v_fmac_f32_e32 v185, v67, v23
	v_fmac_f32_e32 v186, v75, v23
	v_fmac_f32_e32 v187, v83, v23
	ds_read_b128 v[16:19], v15 offset:1280
	ds_read_b128 v[20:23], v15 offset:1296
	s_waitcnt lgkmcnt(2)
	v_fmac_f32_e32 v188, v60, v24
	v_fmac_f32_e32 v189, v68, v24
	v_fmac_f32_e32 v190, v76, v24
	v_fmac_f32_e32 v188, v61, v25
	v_fmac_f32_e32 v189, v69, v25
	v_fmac_f32_e32 v190, v77, v25
	v_fmac_f32_e32 v188, v62, v26
	v_fmac_f32_e32 v189, v70, v26
	v_fmac_f32_e32 v190, v78, v26
	v_fmac_f32_e32 v188, v63, v27
	v_fmac_f32_e32 v189, v71, v27
	v_fmac_f32_e32 v190, v79, v27
	v_fmac_f32_e32 v188, v64, v28
	v_fmac_f32_e32 v189, v72, v28
	v_fmac_f32_e32 v190, v80, v28
	v_fmac_f32_e32 v188, v65, v29
	v_fmac_f32_e32 v189, v73, v29
	v_fmac_f32_e32 v190, v81, v29
	v_fmac_f32_e32 v188, v66, v30
	v_fmac_f32_e32 v189, v74, v30
	v_fmac_f32_e32 v190, v82, v30
	v_fmac_f32_e32 v188, v67, v31
	v_fmac_f32_e32 v189, v75, v31
	v_fmac_f32_e32 v190, v83, v31
	ds_read_b128 v[24:27], v15 offset:1536
	ds_read_b128 v[28:31], v15 offset:1552
	s_waitcnt lgkmcnt(2)
	v_fmac_f32_e32 v191, v60, v16
	v_fmac_f32_e32 v192, v68, v16
	v_fmac_f32_e32 v193, v76, v16
	v_fmac_f32_e32 v191, v61, v17
	v_fmac_f32_e32 v192, v69, v17
	v_fmac_f32_e32 v193, v77, v17
	v_fmac_f32_e32 v191, v62, v18
	v_fmac_f32_e32 v192, v70, v18
	v_fmac_f32_e32 v193, v78, v18
	v_fmac_f32_e32 v191, v63, v19
	v_fmac_f32_e32 v192, v71, v19
	v_fmac_f32_e32 v193, v79, v19
	v_fmac_f32_e32 v191, v64, v20
	v_fmac_f32_e32 v192, v72, v20
	v_fmac_f32_e32 v193, v80, v20
	v_fmac_f32_e32 v191, v65, v21
	v_fmac_f32_e32 v192, v73, v21
	v_fmac_f32_e32 v193, v81, v21
	v_fmac_f32_e32 v191, v66, v22
	v_fmac_f32_e32 v192, v74, v22
	v_fmac_f32_e32 v193, v82, v22
	v_fmac_f32_e32 v191, v67, v23
	v_fmac_f32_e32 v192, v75, v23
	v_fmac_f32_e32 v193, v83, v23
	ds_read_b128 v[16:19], v15 offset:1792
	ds_read_b128 v[20:23], v15 offset:1808
	s_waitcnt lgkmcnt(2)
	v_fmac_f32_e32 v194, v60, v24
	v_fmac_f32_e32 v195, v68, v24
	v_fmac_f32_e32 v196, v76, v24
	v_fmac_f32_e32 v194, v61, v25
	v_fmac_f32_e32 v195, v69, v25
	v_fmac_f32_e32 v196, v77, v25
	v_fmac_f32_e32 v194, v62, v26
	v_fmac_f32_e32 v195, v70, v26
	v_fmac_f32_e32 v196, v78, v26
	v_fmac_f32_e32 v194, v63, v27
	v_fmac_f32_e32 v195, v71, v27
	v_fmac_f32_e32 v196, v79, v27
	v_fmac_f32_e32 v194, v64, v28
	v_fmac_f32_e32 v195, v72, v28
	v_fmac_f32_e32 v196, v80, v28
	v_fmac_f32_e32 v194, v65, v29
	v_fmac_f32_e32 v195, v73, v29
	v_fmac_f32_e32 v196, v81, v29
	v_fmac_f32_e32 v194, v66, v30
	v_fmac_f32_e32 v195, v74, v30
	v_fmac_f32_e32 v196, v82, v30
	v_fmac_f32_e32 v194, v67, v31
	v_fmac_f32_e32 v195, v75, v31
	v_fmac_f32_e32 v196, v83, v31
	ds_read_b128 v[24:27], v15 offset:32
	ds_read_b128 v[28:31], v15 offset:48
	s_waitcnt lgkmcnt(2)
	v_fmac_f32_e32 v197, v60, v16
	v_fmac_f32_e32 v198, v68, v16
	v_fmac_f32_e32 v199, v76, v16
	v_fmac_f32_e32 v197, v61, v17
	v_fmac_f32_e32 v198, v69, v17
	v_fmac_f32_e32 v199, v77, v17
	v_fmac_f32_e32 v197, v62, v18
	v_fmac_f32_e32 v198, v70, v18
	v_fmac_f32_e32 v199, v78, v18
	v_fmac_f32_e32 v197, v63, v19
	v_fmac_f32_e32 v198, v71, v19
	v_fmac_f32_e32 v199, v79, v19
	v_fmac_f32_e32 v197, v64, v20
	v_fmac_f32_e32 v198, v72, v20
	v_fmac_f32_e32 v199, v80, v20
	v_fmac_f32_e32 v197, v65, v21
	v_fmac_f32_e32 v198, v73, v21
	v_fmac_f32_e32 v199, v81, v21
	v_fmac_f32_e32 v197, v66, v22
	v_fmac_f32_e32 v198, v74, v22
	v_fmac_f32_e32 v199, v82, v22
	v_fmac_f32_e32 v197, v67, v23
	v_fmac_f32_e32 v198, v75, v23
	v_fmac_f32_e32 v199, v83, v23
	ds_read_b128 v[60:63], v32 offset:64
	ds_read_b128 v[64:67], v32 offset:80
	ds_read_b128 v[68:71], v33 offset:64
	ds_read_b128 v[72:75], v33 offset:80
	ds_read_b128 v[76:79], v34 offset:64
	ds_read_b128 v[80:83], v34 offset:80
	ds_read_b128 v[16:19], v15 offset:288
	ds_read_b128 v[20:23], v15 offset:304
	s_waitcnt lgkmcnt(8)
	v_fmac_f32_e32 v176, v84, v24
	v_fmac_f32_e32 v177, v92, v24
	v_fmac_f32_e32 v178, v100, v24
	v_fmac_f32_e32 v176, v85, v25
	v_fmac_f32_e32 v177, v93, v25
	v_fmac_f32_e32 v178, v101, v25
	v_fmac_f32_e32 v176, v86, v26
	v_fmac_f32_e32 v177, v94, v26
	v_fmac_f32_e32 v178, v102, v26
	v_fmac_f32_e32 v176, v87, v27
	v_fmac_f32_e32 v177, v95, v27
	v_fmac_f32_e32 v178, v103, v27
	v_fmac_f32_e32 v176, v88, v28
	v_fmac_f32_e32 v177, v96, v28
	v_fmac_f32_e32 v178, v104, v28
	v_fmac_f32_e32 v176, v89, v29
	v_fmac_f32_e32 v177, v97, v29
	v_fmac_f32_e32 v178, v105, v29
	v_fmac_f32_e32 v176, v90, v30
	v_fmac_f32_e32 v177, v98, v30
	v_fmac_f32_e32 v178, v106, v30
	v_fmac_f32_e32 v176, v91, v31
	v_fmac_f32_e32 v177, v99, v31
	v_fmac_f32_e32 v178, v107, v31
	ds_read_b128 v[24:27], v15 offset:544
	ds_read_b128 v[28:31], v15 offset:560
	s_waitcnt lgkmcnt(2)
	v_fmac_f32_e32 v179, v84, v16
	v_fmac_f32_e32 v180, v92, v16
	v_fmac_f32_e32 v181, v100, v16
	v_fmac_f32_e32 v179, v85, v17
	v_fmac_f32_e32 v180, v93, v17
	v_fmac_f32_e32 v181, v101, v17
	v_fmac_f32_e32 v179, v86, v18
	v_fmac_f32_e32 v180, v94, v18
	v_fmac_f32_e32 v181, v102, v18
	v_fmac_f32_e32 v179, v87, v19
	v_fmac_f32_e32 v180, v95, v19
	v_fmac_f32_e32 v181, v103, v19
	v_fmac_f32_e32 v179, v88, v20
	v_fmac_f32_e32 v180, v96, v20
	v_fmac_f32_e32 v181, v104, v20
	v_fmac_f32_e32 v179, v89, v21
	v_fmac_f32_e32 v180, v97, v21
	v_fmac_f32_e32 v181, v105, v21
	v_fmac_f32_e32 v179, v90, v22
	v_fmac_f32_e32 v180, v98, v22
	v_fmac_f32_e32 v181, v106, v22
	v_fmac_f32_e32 v179, v91, v23
	v_fmac_f32_e32 v180, v99, v23
	v_fmac_f32_e32 v181, v107, v23
	ds_read_b128 v[16:19], v15 offset:800
	ds_read_b128 v[20:23], v15 offset:816
	s_waitcnt lgkmcnt(2)
	v_fmac_f32_e32 v182, v84, v24
	v_fmac_f32_e32 v183, v92, v24
	v_fmac_f32_e32 v184, v100, v24
	v_fmac_f32_e32 v182, v85, v25
	v_fmac_f32_e32 v183, v93, v25
	v_fmac_f32_e32 v184, v101, v25
	v_fmac_f32_e32 v182, v86, v26
	v_fmac_f32_e32 v183, v94, v26
	v_fmac_f32_e32 v184, v102, v26
	v_fmac_f32_e32 v182, v87, v27
	v_fmac_f32_e32 v183, v95, v27
	v_fmac_f32_e32 v184, v103, v27
	v_fmac_f32_e32 v182, v88, v28
	v_fmac_f32_e32 v183, v96, v28
	v_fmac_f32_e32 v184, v104, v28
	v_fmac_f32_e32 v182, v89, v29
	v_fmac_f32_e32 v183, v97, v29
	v_fmac_f32_e32 v184, v105, v29
	v_fmac_f32_e32 v182, v90, v30
	v_fmac_f32_e32 v183, v98, v30
	v_fmac_f32_e32 v184, v106, v30
	v_fmac_f32_e32 v182, v91, v31
	v_fmac_f32_e32 v183, v99, v31
	v_fmac_f32_e32 v184, v107, v31
	ds_read_b128 v[24:27], v15 offset:1056
	ds_read_b128 v[28:31], v15 offset:1072
	s_waitcnt lgkmcnt(2)
	v_fmac_f32_e32 v185, v84, v16
	v_fmac_f32_e32 v186, v92, v16
	v_fmac_f32_e32 v187, v100, v16
	v_fmac_f32_e32 v185, v85, v17
	v_fmac_f32_e32 v186, v93, v17
	v_fmac_f32_e32 v187, v101, v17
	v_fmac_f32_e32 v185, v86, v18
	v_fmac_f32_e32 v186, v94, v18
	v_fmac_f32_e32 v187, v102, v18
	v_fmac_f32_e32 v185, v87, v19
	v_fmac_f32_e32 v186, v95, v19
	v_fmac_f32_e32 v187, v103, v19
	v_fmac_f32_e32 v185, v88, v20
	v_fmac_f32_e32 v186, v96, v20
	v_fmac_f32_e32 v187, v104, v20
	v_fmac_f32_e32 v185, v89, v21
	v_fmac_f32_e32 v186, v97, v21
	v_fmac_f32_e32 v187, v105, v21
	v_fmac_f32_e32 v185, v90, v22
	v_fmac_f32_e32 v186, v98, v22
	v_fmac_f32_e32 v187, v106, v22
	v_fmac_f32_e32 v185, v91, v23
	v_fmac_f32_e32 v186, v99, v23
	v_fmac_f32_e32 v187, v107, v23
	ds_read_b128 v[16:19], v15 offset:1312
	ds_read_b128 v[20:23], v15 offset:1328
	s_waitcnt lgkmcnt(2)
	v_fmac_f32_e32 v188, v84, v24
	v_fmac_f32_e32 v189, v92, v24
	v_fmac_f32_e32 v190, v100, v24
	v_fmac_f32_e32 v188, v85, v25
	v_fmac_f32_e32 v189, v93, v25
	v_fmac_f32_e32 v190, v101, v25
	v_fmac_f32_e32 v188, v86, v26
	v_fmac_f32_e32 v189, v94, v26
	v_fmac_f32_e32 v190, v102, v26
	v_fmac_f32_e32 v188, v87, v27
	v_fmac_f32_e32 v189, v95, v27
	v_fmac_f32_e32 v190, v103, v27
	v_fmac_f32_e32 v188, v88, v28
	v_fmac_f32_e32 v189, v96, v28
	v_fmac_f32_e32 v190, v104, v28
	v_fmac_f32_e32 v188, v89, v29
	v_fmac_f32_e32 v189, v97, v29
	v_fmac_f32_e32 v190, v105, v29
	v_fmac_f32_e32 v188, v90, v30
	v_fmac_f32_e32 v189, v98, v30
	v_fmac_f32_e32 v190, v106, v30
	v_fmac_f32_e32 v188, v91, v31
	v_fmac_f32_e32 v189, v99, v31
	v_fmac_f32_e32 v190, v107, v31
	ds_read_b128 v[24:27], v15 offset:1568
	ds_read_b128 v[28:31], v15 offset:1584
	s_waitcnt lgkmcnt(2)
	v_fmac_f32_e32 v191, v84, v16
	v_fmac_f32_e32 v192, v92, v16
	v_fmac_f32_e32 v193, v100, v16
	v_fmac_f32_e32 v191, v85, v17
	v_fmac_f32_e32 v192, v93, v17
	v_fmac_f32_e32 v193, v101, v17
	v_fmac_f32_e32 v191, v86, v18
	v_fmac_f32_e32 v192, v94, v18
	v_fmac_f32_e32 v193, v102, v18
	v_fmac_f32_e32 v191, v87, v19
	v_fmac_f32_e32 v192, v95, v19
	v_fmac_f32_e32 v193, v103, v19
	v_fmac_f32_e32 v191, v88, v20
	v_fmac_f32_e32 v192, v96, v20
	v_fmac_f32_e32 v193, v104, v20
	v_fmac_f32_e32 v191, v89, v21
	v_fmac_f32_e32 v192, v97, v21
	v_fmac_f32_e32 v193, v105, v21
	v_fmac_f32_e32 v191, v90, v22
	v_fmac_f32_e32 v192, v98, v22
	v_fmac_f32_e32 v193, v106, v22
	v_fmac_f32_e32 v191, v91, v23
	v_fmac_f32_e32 v192, v99, v23
	v_fmac_f32_e32 v193, v107, v23
	ds_read_b128 v[16:19], v15 offset:1824
	ds_read_b128 v[20:23], v15 offset:1840
	s_waitcnt lgkmcnt(2)
	v_fmac_f32_e32 v194, v84, v24
	v_fmac_f32_e32 v195, v92, v24
	v_fmac_f32_e32 v196, v100, v24
	v_fmac_f32_e32 v194, v85, v25
	v_fmac_f32_e32 v195, v93, v25
	v_fmac_f32_e32 v196, v101, v25
	v_fmac_f32_e32 v194, v86, v26
	v_fmac_f32_e32 v195, v94, v26
	v_fmac_f32_e32 v196, v102, v26
	v_fmac_f32_e32 v194, v87, v27
	v_fmac_f32_e32 v195, v95, v27
	v_fmac_f32_e32 v196, v103, v27
	v_fmac_f32_e32 v194, v88, v28
	v_fmac_f32_e32 v195, v96, v28
	v_fmac_f32_e32 v196, v104, v28
	v_fmac_f32_e32 v194, v89, v29
	v_fmac_f32_e32 v195, v97, v29
	v_fmac_f32_e32 v196, v105, v29
	v_fmac_f32_e32 v194, v90, v30
	v_fmac_f32_e32 v195, v98, v30
	v_fmac_f32_e32 v196, v106, v30
	v_fmac_f32_e32 v194, v91, v31
	v_fmac_f32_e32 v195, v99, v31
	v_fmac_f32_e32 v196, v107, v31
	ds_read_b128 v[24:27], v15 offset:64
	ds_read_b128 v[28:31], v15 offset:80
	s_waitcnt lgkmcnt(2)
	v_fmac_f32_e32 v197, v84, v16
	v_fmac_f32_e32 v198, v92, v16
	v_fmac_f32_e32 v199, v100, v16
	v_fmac_f32_e32 v197, v85, v17
	v_fmac_f32_e32 v198, v93, v17
	v_fmac_f32_e32 v199, v101, v17
	v_fmac_f32_e32 v197, v86, v18
	v_fmac_f32_e32 v198, v94, v18
	v_fmac_f32_e32 v199, v102, v18
	v_fmac_f32_e32 v197, v87, v19
	v_fmac_f32_e32 v198, v95, v19
	v_fmac_f32_e32 v199, v103, v19
	v_fmac_f32_e32 v197, v88, v20
	v_fmac_f32_e32 v198, v96, v20
	v_fmac_f32_e32 v199, v104, v20
	v_fmac_f32_e32 v197, v89, v21
	v_fmac_f32_e32 v198, v97, v21
	v_fmac_f32_e32 v199, v105, v21
	v_fmac_f32_e32 v197, v90, v22
	v_fmac_f32_e32 v198, v98, v22
	v_fmac_f32_e32 v199, v106, v22
	v_fmac_f32_e32 v197, v91, v23
	v_fmac_f32_e32 v198, v99, v23
	v_fmac_f32_e32 v199, v107, v23
	v_add_u32_e32 v32, 64, v32
	v_add_u32_e32 v33, 64, v33
	v_add_u32_e32 v34, 64, v34
	v_add_u32_e32 v15, 64, v15
	s_add_i32 s17, s17, 1
	s_cmp_lt_u32 s17, 4
	s_cbranch_scc1 .Lsm_qk
	s_waitcnt lgkmcnt(0)
	v_sub_u32_e32 v10, s3, v108
	v_add_u32_e32 v38, 0, v10
	v_cvt_f32_i32_e32 v39, v38
	v_cmp_gt_u32_e32 vcc, s3, v38
	v_mul_f32_e32 v39, v14, v39
	v_fma_f32 v176, v176, s52, -v39
	v_cndmask_b32_e32 v176, v241, v176, vcc
	v_add_u32_e32 v38, 0xffffffc0, v10
	v_cvt_f32_i32_e32 v39, v38
	v_cmp_gt_u32_e32 vcc, s3, v38
	v_mul_f32_e32 v39, v14, v39
	v_fma_f32 v177, v177, s52, -v39
	v_cndmask_b32_e32 v177, v241, v177, vcc
	v_add_u32_e32 v38, 0xffffff80, v10
	v_cvt_f32_i32_e32 v39, v38
	v_cmp_gt_u32_e32 vcc, s3, v38
	v_mul_f32_e32 v39, v14, v39
	v_fma_f32 v178, v178, s52, -v39
	s_and_b64 vcc, s[40:41], vcc
	v_cndmask_b32_e32 v178, v241, v178, vcc
	v_max3_f32 v40, v176, v177, v178
	v_mov_b32_e32 v41, v241
	s_nop 1
	v_mov_b32_dpp v41, v40 quad_perm:[1,0,3,2] row_mask:0xf bank_mask:0xf
	v_max_f32_e32 v40, v40, v41
	v_mov_b32_e32 v41, v241
	s_nop 1
	v_mov_b32_dpp v41, v40 quad_perm:[2,3,0,1] row_mask:0xf bank_mask:0xf
	v_max_f32_e32 v40, v40, v41
	v_mov_b32_e32 v41, v241
	s_nop 1
	v_mov_b32_dpp v41, v40 row_half_mirror row_mask:0xf bank_mask:0xf
	v_max_f32_e32 v40, v40, v41
	v_mov_b32_e32 v41, v241
	s_nop 1
	v_mov_b32_dpp v41, v40 row_mirror row_mask:0xf bank_mask:0xf
	v_max_f32_e32 v40, v40, v41
	v_mov_b32_e32 v41, v241
	s_nop 1
	v_mov_b32_dpp v41, v40 row_bcast:15 row_mask:0xa bank_mask:0xf
	v_max_f32_e32 v40, v40, v41
	v_mov_b32_e32 v41, v241
	s_nop 1
	v_mov_b32_dpp v41, v40 row_bcast:31 row_mask:0xc bank_mask:0xf
	v_max_f32_e32 v40, v40, v41
	s_nop 0
	v_readlane_b32 s4, v40, 63
	s_nop 1
	v_max_f32_e32 v42, s4, v59
	v_sub_f32_e32 v176, v176, v42
	v_mul_f32_e32 v176, 0x3fb8aa3b, v176
	v_sub_f32_e32 v177, v177, v42
	v_mul_f32_e32 v177, 0x3fb8aa3b, v177
	v_sub_f32_e32 v178, v178, v42
	v_mul_f32_e32 v178, 0x3fb8aa3b, v178
	v_exp_f32_e32 v176, v176
	v_exp_f32_e32 v177, v177
	v_exp_f32_e32 v178, v178
	v_add_f32_e32 v43, v176, v177
	v_sub_f32_e32 v38, v59, v42
	v_add_f32_e32 v43, v43, v178
	v_mul_f32_e32 v38, 0x3fb8aa3b, v38
	v_exp_f32_e32 v38, v38
	s_nop 1
	v_add_f32_dpp v43, v43, v43 quad_perm:[1,0,3,2] row_mask:0xf bank_mask:0xf bound_ctrl:1
	s_nop 1
	v_add_f32_dpp v43, v43, v43 quad_perm:[2,3,0,1] row_mask:0xf bank_mask:0xf bound_ctrl:1
	s_nop 1
	v_add_f32_dpp v43, v43, v43 row_half_mirror row_mask:0xf bank_mask:0xf bound_ctrl:1
	s_nop 1
	v_add_f32_dpp v43, v43, v43 row_mirror row_mask:0xf bank_mask:0xf bound_ctrl:1
	v_mov_b32_e32 v41, 0
	s_nop 1
	v_mov_b32_dpp v41, v43 row_bcast:15 row_mask:0xa bank_mask:0xf
	v_add_f32_e32 v43, v43, v41
	v_mov_b32_e32 v41, 0
	s_nop 1
	v_mov_b32_dpp v41, v43 row_bcast:31 row_mask:0xc bank_mask:0xf
	v_add_f32_e32 v43, v43, v41
	s_nop 0
	v_readlane_b32 s5, v43, 63
	s_nop 1
	v_add_f32_e32 v200, s5, v38
	v_add_u32_e32 v38, 1, v10
	v_cvt_f32_i32_e32 v39, v38
	v_cmp_gt_u32_e32 vcc, s3, v38
	v_mul_f32_e32 v39, v14, v39
	v_fma_f32 v179, v179, s52, -v39
	v_cndmask_b32_e32 v179, v241, v179, vcc
	v_add_u32_e32 v38, 0xffffffc1, v10
	v_cvt_f32_i32_e32 v39, v38
	v_cmp_gt_u32_e32 vcc, s3, v38
	v_mul_f32_e32 v39, v14, v39
	v_fma_f32 v180, v180, s52, -v39
	v_cndmask_b32_e32 v180, v241, v180, vcc
	v_add_u32_e32 v38, 0xffffff81, v10
	v_cvt_f32_i32_e32 v39, v38
	v_cmp_gt_u32_e32 vcc, s3, v38
	v_mul_f32_e32 v39, v14, v39
	v_fma_f32 v181, v181, s52, -v39
	s_and_b64 vcc, s[40:41], vcc
	v_cndmask_b32_e32 v181, v241, v181, vcc
	v_max3_f32 v40, v179, v180, v181
	v_mov_b32_e32 v41, v241
	s_nop 1
	v_mov_b32_dpp v41, v40 quad_perm:[1,0,3,2] row_mask:0xf bank_mask:0xf
	v_max_f32_e32 v40, v40, v41
	v_mov_b32_e32 v41, v241
	s_nop 1
	v_mov_b32_dpp v41, v40 quad_perm:[2,3,0,1] row_mask:0xf bank_mask:0xf
	v_max_f32_e32 v40, v40, v41
	v_mov_b32_e32 v41, v241
	s_nop 1
	v_mov_b32_dpp v41, v40 row_half_mirror row_mask:0xf bank_mask:0xf
	v_max_f32_e32 v40, v40, v41
	v_mov_b32_e32 v41, v241
	s_nop 1
	v_mov_b32_dpp v41, v40 row_mirror row_mask:0xf bank_mask:0xf
	v_max_f32_e32 v40, v40, v41
	v_mov_b32_e32 v41, v241
	s_nop 1
	v_mov_b32_dpp v41, v40 row_bcast:15 row_mask:0xa bank_mask:0xf
	v_max_f32_e32 v40, v40, v41
	v_mov_b32_e32 v41, v241
	s_nop 1
	v_mov_b32_dpp v41, v40 row_bcast:31 row_mask:0xc bank_mask:0xf
	v_max_f32_e32 v40, v40, v41
	s_nop 0
	v_readlane_b32 s4, v40, 63
	s_nop 1
	v_max_f32_e32 v42, s4, v59
	v_sub_f32_e32 v179, v179, v42
	v_mul_f32_e32 v179, 0x3fb8aa3b, v179
	v_sub_f32_e32 v180, v180, v42
	v_mul_f32_e32 v180, 0x3fb8aa3b, v180
	v_sub_f32_e32 v181, v181, v42
	v_mul_f32_e32 v181, 0x3fb8aa3b, v181
	v_exp_f32_e32 v179, v179
	v_exp_f32_e32 v180, v180
	v_exp_f32_e32 v181, v181
	v_add_f32_e32 v43, v179, v180
	v_sub_f32_e32 v38, v59, v42
	v_add_f32_e32 v43, v43, v181
	v_mul_f32_e32 v38, 0x3fb8aa3b, v38
	v_exp_f32_e32 v38, v38
	s_nop 1
	v_add_f32_dpp v43, v43, v43 quad_perm:[1,0,3,2] row_mask:0xf bank_mask:0xf bound_ctrl:1
	s_nop 1
	v_add_f32_dpp v43, v43, v43 quad_perm:[2,3,0,1] row_mask:0xf bank_mask:0xf bound_ctrl:1
	s_nop 1
	v_add_f32_dpp v43, v43, v43 row_half_mirror row_mask:0xf bank_mask:0xf bound_ctrl:1
	s_nop 1
	v_add_f32_dpp v43, v43, v43 row_mirror row_mask:0xf bank_mask:0xf bound_ctrl:1
	v_mov_b32_e32 v41, 0
	s_nop 1
	v_mov_b32_dpp v41, v43 row_bcast:15 row_mask:0xa bank_mask:0xf
	v_add_f32_e32 v43, v43, v41
	v_mov_b32_e32 v41, 0
	s_nop 1
	v_mov_b32_dpp v41, v43 row_bcast:31 row_mask:0xc bank_mask:0xf
	v_add_f32_e32 v43, v43, v41
	s_nop 0
	v_readlane_b32 s5, v43, 63
	s_nop 1
	v_add_f32_e32 v201, s5, v38
	v_add_u32_e32 v38, 2, v10
	v_cvt_f32_i32_e32 v39, v38
	v_cmp_gt_u32_e32 vcc, s3, v38
	v_mul_f32_e32 v39, v14, v39
	v_fma_f32 v182, v182, s52, -v39
	v_cndmask_b32_e32 v182, v241, v182, vcc
	v_add_u32_e32 v38, 0xffffffc2, v10
	v_cvt_f32_i32_e32 v39, v38
	v_cmp_gt_u32_e32 vcc, s3, v38
	v_mul_f32_e32 v39, v14, v39
	v_fma_f32 v183, v183, s52, -v39
	v_cndmask_b32_e32 v183, v241, v183, vcc
	v_add_u32_e32 v38, 0xffffff82, v10
	v_cvt_f32_i32_e32 v39, v38
	v_cmp_gt_u32_e32 vcc, s3, v38
	v_mul_f32_e32 v39, v14, v39
	v_fma_f32 v184, v184, s52, -v39
	s_and_b64 vcc, s[40:41], vcc
	v_cndmask_b32_e32 v184, v241, v184, vcc
	v_max3_f32 v40, v182, v183, v184
	v_mov_b32_e32 v41, v241
	s_nop 1
	v_mov_b32_dpp v41, v40 quad_perm:[1,0,3,2] row_mask:0xf bank_mask:0xf
	v_max_f32_e32 v40, v40, v41
	v_mov_b32_e32 v41, v241
	s_nop 1
	v_mov_b32_dpp v41, v40 quad_perm:[2,3,0,1] row_mask:0xf bank_mask:0xf
	v_max_f32_e32 v40, v40, v41
	v_mov_b32_e32 v41, v241
	s_nop 1
	v_mov_b32_dpp v41, v40 row_half_mirror row_mask:0xf bank_mask:0xf
	v_max_f32_e32 v40, v40, v41
	v_mov_b32_e32 v41, v241
	s_nop 1
	v_mov_b32_dpp v41, v40 row_mirror row_mask:0xf bank_mask:0xf
	v_max_f32_e32 v40, v40, v41
	v_mov_b32_e32 v41, v241
	s_nop 1
	v_mov_b32_dpp v41, v40 row_bcast:15 row_mask:0xa bank_mask:0xf
	v_max_f32_e32 v40, v40, v41
	v_mov_b32_e32 v41, v241
	s_nop 1
	v_mov_b32_dpp v41, v40 row_bcast:31 row_mask:0xc bank_mask:0xf
	v_max_f32_e32 v40, v40, v41
	s_nop 0
	v_readlane_b32 s4, v40, 63
	s_nop 1
	v_max_f32_e32 v42, s4, v59
	v_sub_f32_e32 v182, v182, v42
	v_mul_f32_e32 v182, 0x3fb8aa3b, v182
	v_sub_f32_e32 v183, v183, v42
	v_mul_f32_e32 v183, 0x3fb8aa3b, v183
	v_sub_f32_e32 v184, v184, v42
	v_mul_f32_e32 v184, 0x3fb8aa3b, v184
	v_exp_f32_e32 v182, v182
	v_exp_f32_e32 v183, v183
	v_exp_f32_e32 v184, v184
	v_add_f32_e32 v43, v182, v183
	v_sub_f32_e32 v38, v59, v42
	v_add_f32_e32 v43, v43, v184
	v_mul_f32_e32 v38, 0x3fb8aa3b, v38
	v_exp_f32_e32 v38, v38
	s_nop 1
	v_add_f32_dpp v43, v43, v43 quad_perm:[1,0,3,2] row_mask:0xf bank_mask:0xf bound_ctrl:1
	s_nop 1
	v_add_f32_dpp v43, v43, v43 quad_perm:[2,3,0,1] row_mask:0xf bank_mask:0xf bound_ctrl:1
	s_nop 1
	v_add_f32_dpp v43, v43, v43 row_half_mirror row_mask:0xf bank_mask:0xf bound_ctrl:1
	s_nop 1
	v_add_f32_dpp v43, v43, v43 row_mirror row_mask:0xf bank_mask:0xf bound_ctrl:1
	v_mov_b32_e32 v41, 0
	s_nop 1
	v_mov_b32_dpp v41, v43 row_bcast:15 row_mask:0xa bank_mask:0xf
	v_add_f32_e32 v43, v43, v41
	v_mov_b32_e32 v41, 0
	s_nop 1
	v_mov_b32_dpp v41, v43 row_bcast:31 row_mask:0xc bank_mask:0xf
	v_add_f32_e32 v43, v43, v41
	s_nop 0
	v_readlane_b32 s5, v43, 63
	s_nop 1
	v_add_f32_e32 v202, s5, v38
	v_add_u32_e32 v38, 3, v10
	v_cvt_f32_i32_e32 v39, v38
	v_cmp_gt_u32_e32 vcc, s3, v38
	v_mul_f32_e32 v39, v14, v39
	v_fma_f32 v185, v185, s52, -v39
	v_cndmask_b32_e32 v185, v241, v185, vcc
	v_add_u32_e32 v38, 0xffffffc3, v10
	v_cvt_f32_i32_e32 v39, v38
	v_cmp_gt_u32_e32 vcc, s3, v38
	v_mul_f32_e32 v39, v14, v39
	v_fma_f32 v186, v186, s52, -v39
	v_cndmask_b32_e32 v186, v241, v186, vcc
	v_add_u32_e32 v38, 0xffffff83, v10
	v_cvt_f32_i32_e32 v39, v38
	v_cmp_gt_u32_e32 vcc, s3, v38
	v_mul_f32_e32 v39, v14, v39
	v_fma_f32 v187, v187, s52, -v39
	s_and_b64 vcc, s[40:41], vcc
	v_cndmask_b32_e32 v187, v241, v187, vcc
	v_max3_f32 v40, v185, v186, v187
	v_mov_b32_e32 v41, v241
	s_nop 1
	v_mov_b32_dpp v41, v40 quad_perm:[1,0,3,2] row_mask:0xf bank_mask:0xf
	v_max_f32_e32 v40, v40, v41
	v_mov_b32_e32 v41, v241
	s_nop 1
	v_mov_b32_dpp v41, v40 quad_perm:[2,3,0,1] row_mask:0xf bank_mask:0xf
	v_max_f32_e32 v40, v40, v41
	v_mov_b32_e32 v41, v241
	s_nop 1
	v_mov_b32_dpp v41, v40 row_half_mirror row_mask:0xf bank_mask:0xf
	v_max_f32_e32 v40, v40, v41
	v_mov_b32_e32 v41, v241
	s_nop 1
	v_mov_b32_dpp v41, v40 row_mirror row_mask:0xf bank_mask:0xf
	v_max_f32_e32 v40, v40, v41
	v_mov_b32_e32 v41, v241
	s_nop 1
	v_mov_b32_dpp v41, v40 row_bcast:15 row_mask:0xa bank_mask:0xf
	v_max_f32_e32 v40, v40, v41
	v_mov_b32_e32 v41, v241
	s_nop 1
	v_mov_b32_dpp v41, v40 row_bcast:31 row_mask:0xc bank_mask:0xf
	v_max_f32_e32 v40, v40, v41
	s_nop 0
	v_readlane_b32 s4, v40, 63
	s_nop 1
	v_max_f32_e32 v42, s4, v59
	v_sub_f32_e32 v185, v185, v42
	v_mul_f32_e32 v185, 0x3fb8aa3b, v185
	v_sub_f32_e32 v186, v186, v42
	v_mul_f32_e32 v186, 0x3fb8aa3b, v186
	v_sub_f32_e32 v187, v187, v42
	v_mul_f32_e32 v187, 0x3fb8aa3b, v187
	v_exp_f32_e32 v185, v185
	v_exp_f32_e32 v186, v186
	v_exp_f32_e32 v187, v187
	v_add_f32_e32 v43, v185, v186
	v_sub_f32_e32 v38, v59, v42
	v_add_f32_e32 v43, v43, v187
	v_mul_f32_e32 v38, 0x3fb8aa3b, v38
	v_exp_f32_e32 v38, v38
	s_nop 1
	v_add_f32_dpp v43, v43, v43 quad_perm:[1,0,3,2] row_mask:0xf bank_mask:0xf bound_ctrl:1
	s_nop 1
	v_add_f32_dpp v43, v43, v43 quad_perm:[2,3,0,1] row_mask:0xf bank_mask:0xf bound_ctrl:1
	s_nop 1
	v_add_f32_dpp v43, v43, v43 row_half_mirror row_mask:0xf bank_mask:0xf bound_ctrl:1
	s_nop 1
	v_add_f32_dpp v43, v43, v43 row_mirror row_mask:0xf bank_mask:0xf bound_ctrl:1
	v_mov_b32_e32 v41, 0
	s_nop 1
	v_mov_b32_dpp v41, v43 row_bcast:15 row_mask:0xa bank_mask:0xf
	v_add_f32_e32 v43, v43, v41
	v_mov_b32_e32 v41, 0
	s_nop 1
	v_mov_b32_dpp v41, v43 row_bcast:31 row_mask:0xc bank_mask:0xf
	v_add_f32_e32 v43, v43, v41
	s_nop 0
	v_readlane_b32 s5, v43, 63
	s_nop 1
	v_add_f32_e32 v203, s5, v38
	v_add_u32_e32 v38, 4, v10
	v_cvt_f32_i32_e32 v39, v38
	v_cmp_gt_u32_e32 vcc, s3, v38
	v_mul_f32_e32 v39, v14, v39
	v_fma_f32 v188, v188, s52, -v39
	v_cndmask_b32_e32 v188, v241, v188, vcc
	v_add_u32_e32 v38, 0xffffffc4, v10
	v_cvt_f32_i32_e32 v39, v38
	v_cmp_gt_u32_e32 vcc, s3, v38
	v_mul_f32_e32 v39, v14, v39
	v_fma_f32 v189, v189, s52, -v39
	v_cndmask_b32_e32 v189, v241, v189, vcc
	v_add_u32_e32 v38, 0xffffff84, v10
	v_cvt_f32_i32_e32 v39, v38
	v_cmp_gt_u32_e32 vcc, s3, v38
	v_mul_f32_e32 v39, v14, v39
	v_fma_f32 v190, v190, s52, -v39
	s_and_b64 vcc, s[40:41], vcc
	v_cndmask_b32_e32 v190, v241, v190, vcc
	v_max3_f32 v40, v188, v189, v190
	v_mov_b32_e32 v41, v241
	s_nop 1
	v_mov_b32_dpp v41, v40 quad_perm:[1,0,3,2] row_mask:0xf bank_mask:0xf
	v_max_f32_e32 v40, v40, v41
	v_mov_b32_e32 v41, v241
	s_nop 1
	v_mov_b32_dpp v41, v40 quad_perm:[2,3,0,1] row_mask:0xf bank_mask:0xf
	v_max_f32_e32 v40, v40, v41
	v_mov_b32_e32 v41, v241
	s_nop 1
	v_mov_b32_dpp v41, v40 row_half_mirror row_mask:0xf bank_mask:0xf
	v_max_f32_e32 v40, v40, v41
	v_mov_b32_e32 v41, v241
	s_nop 1
	v_mov_b32_dpp v41, v40 row_mirror row_mask:0xf bank_mask:0xf
	v_max_f32_e32 v40, v40, v41
	v_mov_b32_e32 v41, v241
	s_nop 1
	v_mov_b32_dpp v41, v40 row_bcast:15 row_mask:0xa bank_mask:0xf
	v_max_f32_e32 v40, v40, v41
	v_mov_b32_e32 v41, v241
	s_nop 1
	v_mov_b32_dpp v41, v40 row_bcast:31 row_mask:0xc bank_mask:0xf
	v_max_f32_e32 v40, v40, v41
	s_nop 0
	v_readlane_b32 s4, v40, 63
	s_nop 1
	v_max_f32_e32 v42, s4, v59
	v_sub_f32_e32 v188, v188, v42
	v_mul_f32_e32 v188, 0x3fb8aa3b, v188
	v_sub_f32_e32 v189, v189, v42
	v_mul_f32_e32 v189, 0x3fb8aa3b, v189
	v_sub_f32_e32 v190, v190, v42
	v_mul_f32_e32 v190, 0x3fb8aa3b, v190
	v_exp_f32_e32 v188, v188
	v_exp_f32_e32 v189, v189
	v_exp_f32_e32 v190, v190
	v_add_f32_e32 v43, v188, v189
	v_sub_f32_e32 v38, v59, v42
	v_add_f32_e32 v43, v43, v190
	v_mul_f32_e32 v38, 0x3fb8aa3b, v38
	v_exp_f32_e32 v38, v38
	s_nop 1
	v_add_f32_dpp v43, v43, v43 quad_perm:[1,0,3,2] row_mask:0xf bank_mask:0xf bound_ctrl:1
	s_nop 1
	v_add_f32_dpp v43, v43, v43 quad_perm:[2,3,0,1] row_mask:0xf bank_mask:0xf bound_ctrl:1
	s_nop 1
	v_add_f32_dpp v43, v43, v43 row_half_mirror row_mask:0xf bank_mask:0xf bound_ctrl:1
	s_nop 1
	v_add_f32_dpp v43, v43, v43 row_mirror row_mask:0xf bank_mask:0xf bound_ctrl:1
	v_mov_b32_e32 v41, 0
	s_nop 1
	v_mov_b32_dpp v41, v43 row_bcast:15 row_mask:0xa bank_mask:0xf
	v_add_f32_e32 v43, v43, v41
	v_mov_b32_e32 v41, 0
	s_nop 1
	v_mov_b32_dpp v41, v43 row_bcast:31 row_mask:0xc bank_mask:0xf
	v_add_f32_e32 v43, v43, v41
	s_nop 0
	v_readlane_b32 s5, v43, 63
	s_nop 1
	v_add_f32_e32 v204, s5, v38
	v_add_u32_e32 v38, 5, v10
	v_cvt_f32_i32_e32 v39, v38
	v_cmp_gt_u32_e32 vcc, s3, v38
	v_mul_f32_e32 v39, v14, v39
	v_fma_f32 v191, v191, s52, -v39
	v_cndmask_b32_e32 v191, v241, v191, vcc
	v_add_u32_e32 v38, 0xffffffc5, v10
	v_cvt_f32_i32_e32 v39, v38
	v_cmp_gt_u32_e32 vcc, s3, v38
	v_mul_f32_e32 v39, v14, v39
	v_fma_f32 v192, v192, s52, -v39
	v_cndmask_b32_e32 v192, v241, v192, vcc
	v_add_u32_e32 v38, 0xffffff85, v10
	v_cvt_f32_i32_e32 v39, v38
	v_cmp_gt_u32_e32 vcc, s3, v38
	v_mul_f32_e32 v39, v14, v39
	v_fma_f32 v193, v193, s52, -v39
	s_and_b64 vcc, s[40:41], vcc
	v_cndmask_b32_e32 v193, v241, v193, vcc
	v_max3_f32 v40, v191, v192, v193
	v_mov_b32_e32 v41, v241
	s_nop 1
	v_mov_b32_dpp v41, v40 quad_perm:[1,0,3,2] row_mask:0xf bank_mask:0xf
	v_max_f32_e32 v40, v40, v41
	v_mov_b32_e32 v41, v241
	s_nop 1
	v_mov_b32_dpp v41, v40 quad_perm:[2,3,0,1] row_mask:0xf bank_mask:0xf
	v_max_f32_e32 v40, v40, v41
	v_mov_b32_e32 v41, v241
	s_nop 1
	v_mov_b32_dpp v41, v40 row_half_mirror row_mask:0xf bank_mask:0xf
	v_max_f32_e32 v40, v40, v41
	v_mov_b32_e32 v41, v241
	s_nop 1
	v_mov_b32_dpp v41, v40 row_mirror row_mask:0xf bank_mask:0xf
	v_max_f32_e32 v40, v40, v41
	v_mov_b32_e32 v41, v241
	s_nop 1
	v_mov_b32_dpp v41, v40 row_bcast:15 row_mask:0xa bank_mask:0xf
	v_max_f32_e32 v40, v40, v41
	v_mov_b32_e32 v41, v241
	s_nop 1
	v_mov_b32_dpp v41, v40 row_bcast:31 row_mask:0xc bank_mask:0xf
	v_max_f32_e32 v40, v40, v41
	s_nop 0
	v_readlane_b32 s4, v40, 63
	s_nop 1
	v_max_f32_e32 v42, s4, v59
	v_sub_f32_e32 v191, v191, v42
	v_mul_f32_e32 v191, 0x3fb8aa3b, v191
	v_sub_f32_e32 v192, v192, v42
	v_mul_f32_e32 v192, 0x3fb8aa3b, v192
	v_sub_f32_e32 v193, v193, v42
	v_mul_f32_e32 v193, 0x3fb8aa3b, v193
	v_exp_f32_e32 v191, v191
	v_exp_f32_e32 v192, v192
	v_exp_f32_e32 v193, v193
	v_add_f32_e32 v43, v191, v192
	v_sub_f32_e32 v38, v59, v42
	v_add_f32_e32 v43, v43, v193
	v_mul_f32_e32 v38, 0x3fb8aa3b, v38
	v_exp_f32_e32 v38, v38
	s_nop 1
	v_add_f32_dpp v43, v43, v43 quad_perm:[1,0,3,2] row_mask:0xf bank_mask:0xf bound_ctrl:1
	s_nop 1
	v_add_f32_dpp v43, v43, v43 quad_perm:[2,3,0,1] row_mask:0xf bank_mask:0xf bound_ctrl:1
	s_nop 1
	v_add_f32_dpp v43, v43, v43 row_half_mirror row_mask:0xf bank_mask:0xf bound_ctrl:1
	s_nop 1
	v_add_f32_dpp v43, v43, v43 row_mirror row_mask:0xf bank_mask:0xf bound_ctrl:1
	v_mov_b32_e32 v41, 0
	s_nop 1
	v_mov_b32_dpp v41, v43 row_bcast:15 row_mask:0xa bank_mask:0xf
	v_add_f32_e32 v43, v43, v41
	v_mov_b32_e32 v41, 0
	s_nop 1
	v_mov_b32_dpp v41, v43 row_bcast:31 row_mask:0xc bank_mask:0xf
	v_add_f32_e32 v43, v43, v41
	s_nop 0
	v_readlane_b32 s5, v43, 63
	s_nop 1
	v_add_f32_e32 v205, s5, v38
	v_add_u32_e32 v38, 6, v10
	v_cvt_f32_i32_e32 v39, v38
	v_cmp_gt_u32_e32 vcc, s3, v38
	v_mul_f32_e32 v39, v14, v39
	v_fma_f32 v194, v194, s52, -v39
	v_cndmask_b32_e32 v194, v241, v194, vcc
	v_add_u32_e32 v38, 0xffffffc6, v10
	v_cvt_f32_i32_e32 v39, v38
	v_cmp_gt_u32_e32 vcc, s3, v38
	v_mul_f32_e32 v39, v14, v39
	v_fma_f32 v195, v195, s52, -v39
	v_cndmask_b32_e32 v195, v241, v195, vcc
	v_add_u32_e32 v38, 0xffffff86, v10
	v_cvt_f32_i32_e32 v39, v38
	v_cmp_gt_u32_e32 vcc, s3, v38
	v_mul_f32_e32 v39, v14, v39
	v_fma_f32 v196, v196, s52, -v39
	s_and_b64 vcc, s[40:41], vcc
	v_cndmask_b32_e32 v196, v241, v196, vcc
	v_max3_f32 v40, v194, v195, v196
	v_mov_b32_e32 v41, v241
	s_nop 1
	v_mov_b32_dpp v41, v40 quad_perm:[1,0,3,2] row_mask:0xf bank_mask:0xf
	v_max_f32_e32 v40, v40, v41
	v_mov_b32_e32 v41, v241
	s_nop 1
	v_mov_b32_dpp v41, v40 quad_perm:[2,3,0,1] row_mask:0xf bank_mask:0xf
	v_max_f32_e32 v40, v40, v41
	v_mov_b32_e32 v41, v241
	s_nop 1
	v_mov_b32_dpp v41, v40 row_half_mirror row_mask:0xf bank_mask:0xf
	v_max_f32_e32 v40, v40, v41
	v_mov_b32_e32 v41, v241
	s_nop 1
	v_mov_b32_dpp v41, v40 row_mirror row_mask:0xf bank_mask:0xf
	v_max_f32_e32 v40, v40, v41
	v_mov_b32_e32 v41, v241
	s_nop 1
	v_mov_b32_dpp v41, v40 row_bcast:15 row_mask:0xa bank_mask:0xf
	v_max_f32_e32 v40, v40, v41
	v_mov_b32_e32 v41, v241
	s_nop 1
	v_mov_b32_dpp v41, v40 row_bcast:31 row_mask:0xc bank_mask:0xf
	v_max_f32_e32 v40, v40, v41
	s_nop 0
	v_readlane_b32 s4, v40, 63
	s_nop 1
	v_max_f32_e32 v42, s4, v59
	v_sub_f32_e32 v194, v194, v42
	v_mul_f32_e32 v194, 0x3fb8aa3b, v194
	v_sub_f32_e32 v195, v195, v42
	v_mul_f32_e32 v195, 0x3fb8aa3b, v195
	v_sub_f32_e32 v196, v196, v42
	v_mul_f32_e32 v196, 0x3fb8aa3b, v196
	v_exp_f32_e32 v194, v194
	v_exp_f32_e32 v195, v195
	v_exp_f32_e32 v196, v196
	v_add_f32_e32 v43, v194, v195
	v_sub_f32_e32 v38, v59, v42
	v_add_f32_e32 v43, v43, v196
	v_mul_f32_e32 v38, 0x3fb8aa3b, v38
	v_exp_f32_e32 v38, v38
	s_nop 1
	v_add_f32_dpp v43, v43, v43 quad_perm:[1,0,3,2] row_mask:0xf bank_mask:0xf bound_ctrl:1
	s_nop 1
	v_add_f32_dpp v43, v43, v43 quad_perm:[2,3,0,1] row_mask:0xf bank_mask:0xf bound_ctrl:1
	s_nop 1
	v_add_f32_dpp v43, v43, v43 row_half_mirror row_mask:0xf bank_mask:0xf bound_ctrl:1
	s_nop 1
	v_add_f32_dpp v43, v43, v43 row_mirror row_mask:0xf bank_mask:0xf bound_ctrl:1
	v_mov_b32_e32 v41, 0
	s_nop 1
	v_mov_b32_dpp v41, v43 row_bcast:15 row_mask:0xa bank_mask:0xf
	v_add_f32_e32 v43, v43, v41
	v_mov_b32_e32 v41, 0
	s_nop 1
	v_mov_b32_dpp v41, v43 row_bcast:31 row_mask:0xc bank_mask:0xf
	v_add_f32_e32 v43, v43, v41
	s_nop 0
	v_readlane_b32 s5, v43, 63
	s_nop 1
	v_add_f32_e32 v206, s5, v38
	v_add_u32_e32 v38, 7, v10
	v_cvt_f32_i32_e32 v39, v38
	v_cmp_gt_u32_e32 vcc, s3, v38
	v_mul_f32_e32 v39, v14, v39
	v_fma_f32 v197, v197, s52, -v39
	v_cndmask_b32_e32 v197, v241, v197, vcc
	v_add_u32_e32 v38, 0xffffffc7, v10
	v_cvt_f32_i32_e32 v39, v38
	v_cmp_gt_u32_e32 vcc, s3, v38
	v_mul_f32_e32 v39, v14, v39
	v_fma_f32 v198, v198, s52, -v39
	v_cndmask_b32_e32 v198, v241, v198, vcc
	v_add_u32_e32 v38, 0xffffff87, v10
	v_cvt_f32_i32_e32 v39, v38
	v_cmp_gt_u32_e32 vcc, s3, v38
	v_mul_f32_e32 v39, v14, v39
	v_fma_f32 v199, v199, s52, -v39
	s_and_b64 vcc, s[40:41], vcc
	v_cndmask_b32_e32 v199, v241, v199, vcc
	v_max3_f32 v40, v197, v198, v199
	v_mov_b32_e32 v41, v241
	s_nop 1
	v_mov_b32_dpp v41, v40 quad_perm:[1,0,3,2] row_mask:0xf bank_mask:0xf
	v_max_f32_e32 v40, v40, v41
	v_mov_b32_e32 v41, v241
	s_nop 1
	v_mov_b32_dpp v41, v40 quad_perm:[2,3,0,1] row_mask:0xf bank_mask:0xf
	v_max_f32_e32 v40, v40, v41
	v_mov_b32_e32 v41, v241
	s_nop 1
	v_mov_b32_dpp v41, v40 row_half_mirror row_mask:0xf bank_mask:0xf
	v_max_f32_e32 v40, v40, v41
	v_mov_b32_e32 v41, v241
	s_nop 1
	v_mov_b32_dpp v41, v40 row_mirror row_mask:0xf bank_mask:0xf
	v_max_f32_e32 v40, v40, v41
	v_mov_b32_e32 v41, v241
	s_nop 1
	v_mov_b32_dpp v41, v40 row_bcast:15 row_mask:0xa bank_mask:0xf
	v_max_f32_e32 v40, v40, v41
	v_mov_b32_e32 v41, v241
	s_nop 1
	v_mov_b32_dpp v41, v40 row_bcast:31 row_mask:0xc bank_mask:0xf
	v_max_f32_e32 v40, v40, v41
	s_nop 0
	v_readlane_b32 s4, v40, 63
	s_nop 1
	v_max_f32_e32 v42, s4, v59
	v_sub_f32_e32 v197, v197, v42
	v_mul_f32_e32 v197, 0x3fb8aa3b, v197
	v_sub_f32_e32 v198, v198, v42
	v_mul_f32_e32 v198, 0x3fb8aa3b, v198
	v_sub_f32_e32 v199, v199, v42
	v_mul_f32_e32 v199, 0x3fb8aa3b, v199
	v_exp_f32_e32 v197, v197
	v_exp_f32_e32 v198, v198
	v_exp_f32_e32 v199, v199
	v_add_f32_e32 v43, v197, v198
	v_sub_f32_e32 v38, v59, v42
	v_add_f32_e32 v43, v43, v199
	v_mul_f32_e32 v38, 0x3fb8aa3b, v38
	v_exp_f32_e32 v38, v38
	s_nop 1
	v_add_f32_dpp v43, v43, v43 quad_perm:[1,0,3,2] row_mask:0xf bank_mask:0xf bound_ctrl:1
	s_nop 1
	v_add_f32_dpp v43, v43, v43 quad_perm:[2,3,0,1] row_mask:0xf bank_mask:0xf bound_ctrl:1
	s_nop 1
	v_add_f32_dpp v43, v43, v43 row_half_mirror row_mask:0xf bank_mask:0xf bound_ctrl:1
	s_nop 1
	v_add_f32_dpp v43, v43, v43 row_mirror row_mask:0xf bank_mask:0xf bound_ctrl:1
	v_mov_b32_e32 v41, 0
	s_nop 1
	v_mov_b32_dpp v41, v43 row_bcast:15 row_mask:0xa bank_mask:0xf
	v_add_f32_e32 v43, v43, v41
	v_mov_b32_e32 v41, 0
	s_nop 1
	v_mov_b32_dpp v41, v43 row_bcast:31 row_mask:0xc bank_mask:0xf
	v_add_f32_e32 v43, v43, v41
	s_nop 0
	v_readlane_b32 s5, v43, 63
	s_nop 1
	v_add_f32_e32 v207, s5, v38
	v_mov_b32_e32 v208, 0
	v_mov_b32_e32 v209, 0
	v_mov_b32_e32 v210, 0
	v_mov_b32_e32 v211, 0
	v_mov_b32_e32 v212, 0
	v_mov_b32_e32 v213, 0
	v_mov_b32_e32 v214, 0
	v_mov_b32_e32 v215, 0
	v_mov_b32_e32 v35, v54
	ds_read2st64_b32 v[216:217], v35 offset0:0 offset1:64
	ds_read2st64_b32 v[218:219], v35 offset0:1 offset1:65
	ds_read2st64_b32 v[220:221], v35 offset0:2 offset1:66
	ds_read2st64_b32 v[222:223], v35 offset0:3 offset1:67
	s_mov_b32 s17, 0
